# GEMM phases: static s_setprio 1 for the second block of each CU (reset at phase exit)
# baseline (speedup 1.0000x reference)
.LBB0_250:
	s_cmp_lt_i32 s84, 0
	s_cbranch_scc1 .LBB0_348
	s_bitcmp0_b32 s84, 8
	s_cbranch_scc1 .LBB0_253
	s_setprio 1

.LBB0_348:
	s_setprio 0
	s_load_dwordx16 s[12:27], s[0:1], 0x100
	s_cmp_lt_i32 s90, 4
	s_cselect_b64 s[82:83], -1, 0
	s_cmp_gt_i32 s91, 3
	s_cselect_b64 s[0:1], -1, 0
	s_waitcnt lgkmcnt(0)
	v_writelane_b32 v254, s12, 9
	s_and_b64 s[0:1], s[82:83], s[0:1]
	s_andn2_b64 vcc, exec, s[0:1]
	v_writelane_b32 v254, s13, 10
	v_writelane_b32 v254, s14, 11
	v_writelane_b32 v254, s15, 12
	v_writelane_b32 v254, s16, 13
	v_writelane_b32 v254, s17, 14
	v_writelane_b32 v254, s18, 15
	v_writelane_b32 v254, s19, 16
	v_writelane_b32 v254, s20, 17
	v_writelane_b32 v254, s21, 18
	v_writelane_b32 v254, s22, 19
	v_writelane_b32 v254, s23, 20
	v_writelane_b32 v254, s24, 21
	v_writelane_b32 v254, s25, 22
	v_writelane_b32 v254, s26, 23
	v_writelane_b32 v254, s27, 24
	s_cbranch_vccnz .LBB0_698
	s_add_u32 s8, s88, 0xfc00200
	s_addc_u32 s9, s89, 0
	s_andn2_b64 vcc, exec, s[10:11]
	s_cbranch_vccnz .LBB0_403
	s_waitcnt vmcnt(0)
	s_barrier
	s_mov_b64 s[0:1], exec
	v_readlane_b32 s2, v253, 0
	v_readlane_b32 s3, v253, 1
	s_and_b64 s[2:3], s[0:1], s[2:3]
	s_mov_b64 exec, s[2:3]
	s_cbranch_execz .LBB0_402
	v_mov_b32_e32 v16, 0
	s_waitcnt vmcnt(0) expcnt(0) lgkmcnt(0)
	ds_read_b32 v2, v16
	ds_read_b32 v0, v16 offset:4
	s_waitcnt lgkmcnt(1)
	v_cmp_ne_u32_e32 vcc, 0, v2
	s_cbranch_vccnz .LBB0_366
	s_mul_i32 s24, s93, s92
	v_readlane_b32 s2, v253, 2
	s_mul_i32 s24, s24, s2
	s_add_u32 s2, s88, 0xfc00400
	s_addc_u32 s3, s89, 0
	s_add_u32 s4, s88, 0xfc00500
	s_addc_u32 s5, s89, 0
	s_add_u32 s6, s88, 0xfc00600
	s_addc_u32 s7, s89, 0
	s_add_u32 s10, s88, 0xfc00700
	s_addc_u32 s11, s89, 0
	s_add_u32 s12, s88, 0xfc00800
	s_addc_u32 s13, s89, 0
	s_add_u32 s14, s88, 0xfc00900
	s_addc_u32 s15, s89, 0
	s_add_u32 s16, s88, 0xfc00a00
	s_addc_u32 s17, s89, 0
	s_add_u32 s18, s88, 0xfc00b00
	s_addc_u32 s19, s89, 0
	s_add_u32 s20, s88, 0xfc00c00
	s_addc_u32 s21, s89, 0
	s_add_u32 s22, s88, 0xfc00d00
	s_addc_u32 s23, s89, 0
	s_add_u32 s26, s88, 0xfc00e00
	s_addc_u32 s27, s89, 0
	s_add_u32 s28, s88, 0xfc00f00
	s_addc_u32 s29, s89, 0
	s_add_u32 s30, s88, 0xfc01000
	s_addc_u32 s31, s89, 0
	s_add_u32 s34, s88, 0xfc01100
	s_addc_u32 s35, s89, 0
	s_add_u32 s52, s88, 0xfc01200
	s_addc_u32 s53, s89, 0
	s_add_u32 s54, s88, 0xfc01300
	s_addc_u32 s55, s89, 0
	s_mov_b32 s25, 1
	s_branch .LBB0_354

.Lp5_gemm:
	s_bitcmp0_b32 s84, 8
	s_cbranch_scc1 .LBB0_815
	s_setprio 1

.LBB0_822:
	s_setprio 0
	s_bitcmp1_b32 s84, 8
	s_cbranch_scc1 .LBB0_845

.LBB0_963:
	v_mov_b32_e32 v252, 0
	ds_read_b64 v[250:251], v252
	s_waitcnt lgkmcnt(0)
	s_cmp_lt_i32 s84, 0
	s_cbranch_scc1 .LBB0_979
	s_bitcmp0_b32 s84, 8
	s_cbranch_scc1 .LBB0_966
	s_setprio 1

.LBB0_979:
	s_setprio 0
	s_cmp_lt_i32 s90, 9
	s_cselect_b64 s[2:3], -1, 0
	s_cmp_gt_i32 s91, 8
	s_cselect_b64 s[4:5], -1, 0
	s_and_b64 s[4:5], s[2:3], s[4:5]
	s_andn2_b64 vcc, exec, s[4:5]
	s_cbranch_vccnz .LBB0_1056
	s_andn2_b64 vcc, exec, s[0:1]
	s_cbranch_vccnz .LBB0_1034
	s_waitcnt vmcnt(0)
	s_barrier
	s_mov_b64 s[0:1], exec
	v_readlane_b32 s4, v253, 0
	v_readlane_b32 s5, v253, 1
	s_and_b64 s[4:5], s[0:1], s[4:5]
	s_mov_b64 exec, s[4:5]
	s_cbranch_execz .LBB0_1033
	v_mov_b32_e32 v0, 0
	s_waitcnt vmcnt(0) expcnt(0) lgkmcnt(0)
	ds_read_b32 v2, v0
	ds_read_b32 v1, v0 offset:4
	s_add_u32 s4, s88, 0xfc00200
	s_addc_u32 s5, s89, 0
	s_waitcnt lgkmcnt(1)
	v_cmp_ne_u32_e32 vcc, 0, v2
	s_cbranch_vccnz .LBB0_997
	s_mul_i32 s33, s93, s92
	v_readlane_b32 s6, v253, 2
	s_mul_i32 s33, s33, s6
	s_add_u32 s6, s88, 0xfc00400
	s_addc_u32 s7, s89, 0
	s_add_u32 s8, s88, 0xfc00500
	s_addc_u32 s9, s89, 0
	s_add_u32 s10, s88, 0xfc00600
	s_addc_u32 s11, s89, 0
	s_add_u32 s12, s88, 0xfc00700
	s_addc_u32 s13, s89, 0
	s_add_u32 s14, s88, 0xfc00800
	s_addc_u32 s15, s89, 0
	s_add_u32 s16, s88, 0xfc00900
	s_addc_u32 s17, s89, 0
	s_add_u32 s18, s88, 0xfc00a00
	s_addc_u32 s19, s89, 0
	s_add_u32 s20, s88, 0xfc00b00
	s_addc_u32 s21, s89, 0
	s_add_u32 s22, s88, 0xfc00c00
	s_addc_u32 s23, s89, 0
	s_add_u32 s24, s88, 0xfc00d00
	s_addc_u32 s25, s89, 0
	s_add_u32 s26, s88, 0xfc00e00
	s_addc_u32 s27, s89, 0
	s_add_u32 s28, s88, 0xfc00f00
	s_addc_u32 s29, s89, 0
	s_add_u32 s30, s88, 0xfc01000
	s_addc_u32 s31, s89, 0
	s_add_u32 s34, s88, 0xfc01100
	s_addc_u32 s35, s89, 0
	s_add_u32 s36, s88, 0xfc01200
	s_addc_u32 s37, s89, 0
	s_add_u32 s38, s88, 0xfc01300
	s_addc_u32 s39, s89, 0
	s_mov_b32 s46, 1
	s_branch .LBB0_985

.LBB0_1121:
	s_setprio 0
	s_cmp_lt_i32 s90, 11
	s_cselect_b64 s[2:3], -1, 0
	s_cmp_gt_i32 s91, 10
	s_cselect_b64 s[4:5], -1, 0
	s_and_b64 s[4:5], s[2:3], s[4:5]
	s_andn2_b64 vcc, exec, s[4:5]
	s_cbranch_vccnz .LBB0_1180
	s_andn2_b64 vcc, exec, s[0:1]
	s_cbranch_vccnz .LBB0_1176
	s_waitcnt vmcnt(0)
	s_barrier
	s_mov_b64 s[0:1], exec
	v_readlane_b32 s4, v253, 0
	v_readlane_b32 s5, v253, 1
	s_and_b64 s[4:5], s[0:1], s[4:5]
	s_mov_b64 exec, s[4:5]
	s_cbranch_execz .LBB0_1175
	v_mov_b32_e32 v0, 0
	s_waitcnt vmcnt(0) expcnt(0) lgkmcnt(0)
	ds_read_b32 v2, v0
	ds_read_b32 v1, v0 offset:4
	s_add_u32 s4, s88, 0xfc00200
	s_addc_u32 s5, s89, 0
	s_waitcnt lgkmcnt(1)
	v_cmp_ne_u32_e32 vcc, 0, v2
	s_cbranch_vccnz .LBB0_1139
	s_mul_i32 s33, s93, s92
	v_readlane_b32 s6, v253, 2
	s_mul_i32 s33, s33, s6
	s_add_u32 s6, s88, 0xfc00400
	s_addc_u32 s7, s89, 0
	s_add_u32 s8, s88, 0xfc00500
	s_addc_u32 s9, s89, 0
	s_add_u32 s10, s88, 0xfc00600
	s_addc_u32 s11, s89, 0
	s_add_u32 s12, s88, 0xfc00700
	s_addc_u32 s13, s89, 0
	s_add_u32 s14, s88, 0xfc00800
	s_addc_u32 s15, s89, 0
	s_add_u32 s16, s88, 0xfc00900
	s_addc_u32 s17, s89, 0
	s_add_u32 s18, s88, 0xfc00a00
	s_addc_u32 s19, s89, 0
	s_add_u32 s20, s88, 0xfc00b00
	s_addc_u32 s21, s89, 0
	s_add_u32 s22, s88, 0xfc00c00
	s_addc_u32 s23, s89, 0
	s_add_u32 s24, s88, 0xfc00d00
	s_addc_u32 s25, s89, 0
	s_add_u32 s26, s88, 0xfc00e00
	s_addc_u32 s27, s89, 0
	s_add_u32 s28, s88, 0xfc00f00
	s_addc_u32 s29, s89, 0
	s_add_u32 s30, s88, 0xfc01000
	s_addc_u32 s31, s89, 0
	s_add_u32 s34, s88, 0xfc01100
	s_addc_u32 s35, s89, 0
	s_add_u32 s36, s88, 0xfc01200
	s_addc_u32 s37, s89, 0
	s_add_u32 s38, s88, 0xfc01300
	s_addc_u32 s39, s89, 0
	s_mov_b32 s46, 1
	s_branch .LBB0_1127

.LBB0_1573:
	s_setprio 0
	v_readlane_b32 s52, v253, 55
	v_readlane_b32 s62, v254, 1
	v_readlane_b32 s63, v254, 2
	v_readlane_b32 s64, v254, 3
	v_readlane_b32 s65, v254, 4
	v_readlane_b32 s66, v254, 5
	v_readlane_b32 s67, v254, 6
	v_readlane_b32 s53, v253, 56
	v_readlane_b32 s54, v253, 57
	v_readlane_b32 s55, v253, 58
	v_readlane_b32 s56, v253, 59
	v_readlane_b32 s57, v253, 60
	v_readlane_b32 s58, v253, 61
	v_readlane_b32 s59, v253, 62
	v_readlane_b32 s60, v253, 63
	v_readlane_b32 s61, v254, 0

.LBB0_1777:
	s_setprio 0
	s_cmp_lt_i32 s90, 15
	s_cselect_b64 s[2:3], -1, 0
	s_cmp_gt_i32 s91, 14
	s_cselect_b64 s[4:5], -1, 0
	s_and_b64 s[4:5], s[2:3], s[4:5]
	s_andn2_b64 vcc, exec, s[4:5]
	s_cbranch_vccnz .LBB0_1836
	s_andn2_b64 vcc, exec, s[0:1]
	s_cbranch_vccnz .LBB0_1832
	s_waitcnt vmcnt(0)
	s_waitcnt lgkmcnt(0)
	s_barrier
	s_mov_b64 s[0:1], exec
	v_readlane_b32 s4, v253, 0
	v_readlane_b32 s5, v253, 1
	s_and_b64 s[4:5], s[0:1], s[4:5]
	s_mov_b64 exec, s[4:5]
	s_cbranch_execz .LBB0_1831
	v_mov_b32_e32 v0, 0
	s_waitcnt vmcnt(0) expcnt(0) lgkmcnt(0)
	ds_read_b32 v2, v0
	ds_read_b32 v1, v0 offset:4
	s_add_u32 s4, s88, 0xfc00200
	s_addc_u32 s5, s89, 0
	s_waitcnt lgkmcnt(1)
	v_cmp_ne_u32_e32 vcc, 0, v2
	s_cbranch_vccnz .LBB0_1795
	s_mul_i32 s33, s93, s92
	v_readlane_b32 s6, v253, 2
	s_mul_i32 s33, s33, s6
	s_add_u32 s6, s88, 0xfc00400
	s_addc_u32 s7, s89, 0
	s_add_u32 s8, s88, 0xfc00500
	s_addc_u32 s9, s89, 0
	s_add_u32 s10, s88, 0xfc00600
	s_addc_u32 s11, s89, 0
	s_add_u32 s12, s88, 0xfc00700
	s_addc_u32 s13, s89, 0
	s_add_u32 s14, s88, 0xfc00800
	s_addc_u32 s15, s89, 0
	s_add_u32 s16, s88, 0xfc00900
	s_addc_u32 s17, s89, 0
	s_add_u32 s18, s88, 0xfc00a00
	s_addc_u32 s19, s89, 0
	s_add_u32 s20, s88, 0xfc00b00
	s_addc_u32 s21, s89, 0
	s_add_u32 s22, s88, 0xfc00c00
	s_addc_u32 s23, s89, 0
	s_add_u32 s24, s88, 0xfc00d00
	s_addc_u32 s25, s89, 0
	s_add_u32 s26, s88, 0xfc00e00
	s_addc_u32 s27, s89, 0
	s_add_u32 s28, s88, 0xfc00f00
	s_addc_u32 s29, s89, 0
	s_add_u32 s30, s88, 0xfc01000
	s_addc_u32 s31, s89, 0
	s_add_u32 s34, s88, 0xfc01100
	s_addc_u32 s35, s89, 0
	s_add_u32 s36, s88, 0xfc01200
	s_addc_u32 s37, s89, 0
	s_add_u32 s38, s88, 0xfc01300
	s_addc_u32 s39, s89, 0
	s_mov_b32 s46, 1
	s_branch .LBB0_1783

.LBB0_1907:
	s_setprio 0
	s_cmp_lt_i32 s90, 17
	s_cselect_b64 s[2:3], -1, 0
	s_cmp_gt_i32 s91, 16
	s_cselect_b64 s[4:5], -1, 0
	s_and_b64 s[4:5], s[2:3], s[4:5]
	s_andn2_b64 vcc, exec, s[4:5]
	s_cbranch_vccnz .LBB0_1984
	s_andn2_b64 vcc, exec, s[0:1]
	s_cbranch_vccnz .LBB0_1962
	s_waitcnt vmcnt(0)
	s_waitcnt lgkmcnt(0)
	s_barrier
	s_mov_b64 s[0:1], exec
	v_readlane_b32 s4, v253, 0
	v_readlane_b32 s5, v253, 1
	s_and_b64 s[4:5], s[0:1], s[4:5]
	s_mov_b64 exec, s[4:5]
	s_cbranch_execz .LBB0_1961
	v_mov_b32_e32 v0, 0
	s_waitcnt vmcnt(0) expcnt(0) lgkmcnt(0)
	ds_read_b32 v2, v0
	ds_read_b32 v1, v0 offset:4
	s_add_u32 s4, s88, 0xfc00200
	s_addc_u32 s5, s89, 0
	s_waitcnt lgkmcnt(1)
	v_cmp_ne_u32_e32 vcc, 0, v2
	s_cbranch_vccnz .LBB0_1925
	s_mul_i32 s33, s93, s92
	v_readlane_b32 s6, v253, 2
	s_mul_i32 s33, s33, s6
	s_add_u32 s6, s88, 0xfc00400
	s_addc_u32 s7, s89, 0
	s_add_u32 s8, s88, 0xfc00500
	s_addc_u32 s9, s89, 0
	s_add_u32 s10, s88, 0xfc00600
	s_addc_u32 s11, s89, 0
	s_add_u32 s12, s88, 0xfc00700
	s_addc_u32 s13, s89, 0
	s_add_u32 s14, s88, 0xfc00800
	s_addc_u32 s15, s89, 0
	s_add_u32 s16, s88, 0xfc00900
	s_addc_u32 s17, s89, 0
	s_add_u32 s18, s88, 0xfc00a00
	s_addc_u32 s19, s89, 0
	s_add_u32 s20, s88, 0xfc00b00
	s_addc_u32 s21, s89, 0
	s_add_u32 s22, s88, 0xfc00c00
	s_addc_u32 s23, s89, 0
	s_add_u32 s24, s88, 0xfc00d00
	s_addc_u32 s25, s89, 0
	s_add_u32 s26, s88, 0xfc00e00
	s_addc_u32 s27, s89, 0
	s_add_u32 s28, s88, 0xfc00f00
	s_addc_u32 s29, s89, 0
	s_add_u32 s30, s88, 0xfc01000
	s_addc_u32 s31, s89, 0
	s_add_u32 s34, s88, 0xfc01100
	s_addc_u32 s35, s89, 0
	s_add_u32 s36, s88, 0xfc01200
	s_addc_u32 s37, s89, 0
	s_add_u32 s38, s88, 0xfc01300
	s_addc_u32 s39, s89, 0
	s_mov_b32 s46, 1
	s_branch .LBB0_1913

.LBB0_2049:
	s_setprio 0
	s_cmp_lt_i32 s90, 19
	s_cselect_b64 s[2:3], -1, 0
	s_cmp_gt_i32 s91, 18
	s_cselect_b64 s[4:5], -1, 0
	s_and_b64 s[2:3], s[2:3], s[4:5]
	s_andn2_b64 vcc, exec, s[2:3]
	s_cbranch_vccnz .LBB0_2107
	s_andn2_b64 vcc, exec, s[0:1]
	s_cbranch_vccnz .LBB0_2104
	s_waitcnt vmcnt(0)
	s_waitcnt lgkmcnt(0)
	s_barrier
	s_mov_b64 s[0:1], exec
	v_readlane_b32 s2, v253, 0
	v_readlane_b32 s3, v253, 1
	s_and_b64 s[2:3], s[0:1], s[2:3]
	s_mov_b64 exec, s[2:3]
	s_cbranch_execz .LBB0_2103
	v_mov_b32_e32 v0, 0
	s_waitcnt vmcnt(0) expcnt(0) lgkmcnt(0)
	ds_read_b32 v2, v0
	ds_read_b32 v1, v0 offset:4
	s_add_u32 s2, s88, 0xfc00200
	s_addc_u32 s3, s89, 0
	s_waitcnt lgkmcnt(1)
	v_cmp_ne_u32_e32 vcc, 0, v2
	s_cbranch_vccnz .LBB0_2067
	s_mul_i32 s33, s93, s92
	v_readlane_b32 s4, v253, 2
	s_mul_i32 s33, s33, s4
	s_add_u32 s4, s88, 0xfc00400
	s_addc_u32 s5, s89, 0
	s_add_u32 s6, s88, 0xfc00500
	s_addc_u32 s7, s89, 0
	s_add_u32 s8, s88, 0xfc00600
	s_addc_u32 s9, s89, 0
	s_add_u32 s10, s88, 0xfc00700
	s_addc_u32 s11, s89, 0
	s_add_u32 s12, s88, 0xfc00800
	s_addc_u32 s13, s89, 0
	s_add_u32 s14, s88, 0xfc00900
	s_addc_u32 s15, s89, 0
	s_add_u32 s16, s88, 0xfc00a00
	s_addc_u32 s17, s89, 0
	s_add_u32 s18, s88, 0xfc00b00
	s_addc_u32 s19, s89, 0
	s_add_u32 s20, s88, 0xfc00c00
	s_addc_u32 s21, s89, 0
	s_add_u32 s22, s88, 0xfc00d00
	s_addc_u32 s23, s89, 0
	s_add_u32 s24, s88, 0xfc00e00
	s_addc_u32 s25, s89, 0
	s_add_u32 s26, s88, 0xfc00f00
	s_addc_u32 s27, s89, 0
	s_add_u32 s28, s88, 0xfc01000
	s_addc_u32 s29, s89, 0
	s_add_u32 s30, s88, 0xfc01100
	s_addc_u32 s31, s89, 0
	s_add_u32 s34, s88, 0xfc01200
	s_addc_u32 s35, s89, 0
	s_add_u32 s36, s88, 0xfc01300
	s_addc_u32 s37, s89, 0
	s_mov_b32 s44, 1
	s_branch .LBB0_2055
